# scan P2 waves: the decay-prefix blocks a wave needs are requested together with the iteration's first LDS reads (separate registers), one LDS round trip instead of up to five
# speedup vs baseline: 1.0094x; 1.0094x over previous
; #define LAS __attribute__((address_space(3)))
; __device__ __forceinline__ void scan_phase(LAS unsigned char* lds, const bf16_t* R, const bf16_t* Kb, const bf16_t* V, const bf16_t* WA, const float* k_k, const float* k_a, bf16_t* Y, int G, int bid, int tid) {
;     ...
;                 LAS unsigned char* buf = lds + (it & 1) * CK_BUF;
;                 const LAS unsigned char* ldp = lds + CK_LD + (it & 1) * 4096 + 16 * pj;
;                 const LAS unsigned char* stp = lds + CK_STG + (it & 1) * CK_STG_SZ + (pt * 64 + 4 * pj) * 4;
;                 f32x4 nkk = *(const LAS f32x4*)(stp), be = *(const LAS f32x4*)(stp + 4096), kp = *(const LAS f32x4*)(stp + 8192), rf = *(const LAS f32x4*)(stp + 12288), lf = *(const LAS f32x4*)(ldp + pt * 256);
;                 unsigned vsave = *(const LAS unsigned*)(lds + CK_STG + (it & 1) * CK_STG_SZ + 16384 + (pt * 16 + pj) * 4);
;                 asm volatile("" : "+v"(nkk), "+v"(be), "+v"(kp), "+v"(rf), "+v"(lf), "+v"(vsave));
;                 f32x4 Gc = (f32x4){0.f, 0.f, 0.f, 0.f};
;                 const int w4 = 4 * wq;
; #pragma unroll
;                 for (int s4 = 0; s4 < 16; s4 += 4) {
;                     if (s4 <= w4) {
;                         f32x4 x0 = *(const LAS f32x4*)(ldp + (s4 + 0) * 256), x1 = *(const LAS f32x4*)(ldp + (s4 + 1) * 256), x2 = *(const LAS f32x4*)(ldp + (s4 + 2) * 256), x3 = *(const LAS f32x4*)(ldp + (s4 + 3) * 256);
;                         asm volatile("" : "+v"(x0), "+v"(x1), "+v"(x2), "+v"(x3));
;                         if (s4 < w4) Gc += (x0 + x1) + (x2 + x3);
;                         else { const f32x4 z4 = (f32x4){0.f, 0.f, 0.f, 0.f};
;                             Gc += (s4 + 0 <= pt) ? x0 : z4; Gc += (s4 + 1 <= pt) ? x1 : z4; Gc += (s4 + 2 <= pt) ? x2 : z4; Gc += (s4 + 3 <= pt) ? x3 : z4; }
;                     }
;                 }
.LBB0_921:
	s_cmp_ge_u32 s60, 0x7f8000
	s_cselect_b64 s[0:1], -1, 0
	s_or_b64 s[0:1], s[58:59], s[0:1]
	s_and_b64 vcc, exec, s[0:1]
	s_cbranch_vccnz .LBB0_949
	s_and_b32 s78, s62, 1
	s_mul_i32 s0, s78, 0x4400
	s_add_i32 s96, s0, 0
	v_lshl_add_u32 v73, s78, 12, v160
	v_add3_u32 v3, s96, v162, v102
	v_add3_u32 v1, s96, v161, v104
	v_add_u32_e32 v2, v73, v161
	ds_read_b32 v72, v3 offset:61440
	ds_read_b128 v[44:47], v2 offset:31744
	ds_read_b128 v[36:39], v1 offset:57344
	ds_read_b128 v[28:31], v1 offset:53248
	ds_read_b128 v[32:35], v1 offset:49152
	ds_read_b128 v[40:43], v1 offset:45056
	ds_read_b128 v[52:55], v73 offset:32512
	ds_read_b128 v[56:59], v73 offset:32256
	ds_read_b128 v[60:63], v73 offset:32000
	ds_read_b128 v[64:67], v73 offset:31744
	s_andn2_b64 vcc, exec, s[84:85]
	s_cbranch_vccnz .Lmy_p2h_done
	ds_read_b128 v[200:203], v73 offset:33536
	ds_read_b128 v[204:207], v73 offset:33280
	ds_read_b128 v[208:211], v73 offset:33024
	ds_read_b128 v[212:215], v73 offset:32768
	s_andn2_b64 vcc, exec, s[88:89]
	s_cbranch_vccnz .Lmy_p2h_done
	ds_read_b128 v[216:219], v73 offset:34560
	ds_read_b128 v[220:223], v73 offset:34304
	ds_read_b128 v[224:227], v73 offset:34048
	ds_read_b128 v[228:231], v73 offset:33792
	s_andn2_b64 vcc, exec, s[92:93]
	s_cbranch_vccnz .Lmy_p2h_done
	ds_read_b128 v[232:235], v73 offset:35584
	ds_read_b128 v[236:239], v73 offset:35328
	ds_read_b128 v[240:243], v73 offset:35072
	ds_read_b128 v[244:247], v73 offset:34816
.Lmy_p2h_done:
	s_and_b64 vcc, exec, s[52:53]
	s_waitcnt lgkmcnt(0)
	s_cbranch_vccnz .LBB0_925
	s_andn2_b64 vcc, exec, s[82:83]
	s_cbranch_vccnz .LBB0_926
	v_pk_add_f32 v[2:3], v[66:67], v[62:63]
	v_pk_add_f32 v[48:49], v[64:65], v[60:61]
	v_pk_add_f32 v[50:51], v[58:59], v[54:55]
	v_pk_add_f32 v[68:69], v[56:57], v[52:53]
	v_pk_add_f32 v[2:3], v[2:3], v[50:51]
	v_pk_add_f32 v[48:49], v[48:49], v[68:69]
	v_pk_add_f32 v[50:51], v[2:3], 0 op_sel_hi:[1,0]
	v_pk_add_f32 v[48:49], v[48:49], 0 op_sel_hi:[1,0]
	s_cbranch_execz .LBB0_927
	s_branch .LBB0_928
